# v62 + P1 block gates: L1-only invalidate (sc0); the XCD L2 was invalidated at the P0->P1 barrier and cannot have fetched a w_in^T block before its publication
# speedup vs baseline: 1.0051x; 1.0051x over previous
;     __device__ __forceinline__ void gate(const pg8::Unit& u, bool inv) const {
;     ...
;         if (u.pn < NB0 || GATE_OFF) return;
;         const unsigned* c = blk + 16 * u.pn;
;         unsigned v;
;         asm volatile("s_load_dword %0, %1, 0x0 glc\n\ts_waitcnt lgkmcnt(0)" : "=s"(v) : "s"(c) : "memory");
;         if (v < 32u) {
;             for (unsigned sp = 0; sp < (1u << 17); ++sp) {
;                 unsigned vv;
;                 asm volatile("global_load_dword %0, %1, off sc1\n\ts_waitcnt vmcnt(0)" : "=v"(vv) : "v"(c) : "memory");
;                 if ((unsigned)__builtin_amdgcn_readfirstlane(vv) >= 32u) break;
;                 __builtin_amdgcn_s_sleep(8);
;             }
;         }
;         if (inv) asm volatile("buffer_inv sc1" ::: "memory");
.LBB0_300:
	s_andn2_b64 vcc, exec, s[6:7]
	s_cbranch_vccnz .LBB0_302
	buffer_inv sc0
